# P3 prompt attention: two alternating LDS K/V tile buffers, one barrier per key tile instead of two; GEMM loop barrier at group 13
# speedup vs baseline: 1.2499x; 1.0036x over previous
.LBB0_203:
	ds_read_b128 v[226:229], v157
	ds_read_b128 v[230:233], v158
	ds_read_b128 v[234:237], v159
	s_waitcnt lgkmcnt(5)
	v_mfma_f32_16x16x32_bf16 v[124:127], v[214:217], v[174:177], v[124:127]
	v_mfma_f32_16x16x32_bf16 v[120:123], v[214:217], v[178:181], v[120:123]
	v_mfma_f32_16x16x32_bf16 v[116:119], v[214:217], v[182:185], v[116:119]
	v_mfma_f32_16x16x32_bf16 v[112:115], v[214:217], v[186:189], v[112:115]
	ds_read_b128 v[238:241], v160
	s_waitcnt lgkmcnt(5)
	v_mfma_f32_16x16x32_bf16 v[108:111], v[218:221], v[174:177], v[108:111]
	v_mfma_f32_16x16x32_bf16 v[104:107], v[218:221], v[178:181], v[104:107]
	v_mfma_f32_16x16x32_bf16 v[100:103], v[218:221], v[182:185], v[100:103]
	v_mfma_f32_16x16x32_bf16 v[96:99], v[218:221], v[186:189], v[96:99]
	ds_read_b128 v[242:245], v161
	ds_read_b128 v[190:193], v153 offset:33792
	s_waitcnt lgkmcnt(6)
	v_mfma_f32_16x16x32_bf16 v[92:95], v[222:225], v[174:177], v[92:95]
	v_mfma_f32_16x16x32_bf16 v[88:91], v[222:225], v[178:181], v[88:91]
	v_mfma_f32_16x16x32_bf16 v[84:87], v[222:225], v[182:185], v[84:87]
	v_mfma_f32_16x16x32_bf16 v[80:83], v[222:225], v[186:189], v[80:83]
	ds_read_b128 v[214:217], v154 offset:1024
	ds_read_b128 v[194:197], v153 offset:35840
	s_waitcnt lgkmcnt(7)
	v_mfma_f32_16x16x32_bf16 v[76:79], v[226:229], v[174:177], v[76:79]
	v_mfma_f32_16x16x32_bf16 v[72:75], v[226:229], v[178:181], v[72:75]
	v_mfma_f32_16x16x32_bf16 v[68:71], v[226:229], v[182:185], v[68:71]
	v_mfma_f32_16x16x32_bf16 v[64:67], v[226:229], v[186:189], v[64:67]
	ds_read_b128 v[218:221], v155 offset:1024
	ds_read_b128 v[198:201], v153 offset:37888
	s_waitcnt lgkmcnt(8)
	v_mfma_f32_16x16x32_bf16 v[60:63], v[230:233], v[174:177], v[60:63]
	v_mfma_f32_16x16x32_bf16 v[56:59], v[230:233], v[178:181], v[56:59]
	v_mfma_f32_16x16x32_bf16 v[52:55], v[230:233], v[182:185], v[52:55]
	v_mfma_f32_16x16x32_bf16 v[48:51], v[230:233], v[186:189], v[48:51]
	ds_read_b128 v[222:225], v156 offset:1024
	ds_read_b128 v[210:213], v153 offset:39936
	s_waitcnt lgkmcnt(9)
	v_mfma_f32_16x16x32_bf16 v[44:47], v[234:237], v[174:177], v[44:47]
	v_mfma_f32_16x16x32_bf16 v[40:43], v[234:237], v[178:181], v[40:43]
	v_mfma_f32_16x16x32_bf16 v[36:39], v[234:237], v[182:185], v[36:39]
	v_mfma_f32_16x16x32_bf16 v[32:35], v[234:237], v[186:189], v[32:35]
	ds_read_b128 v[226:229], v157 offset:1024
	s_waitcnt lgkmcnt(9)
	v_mfma_f32_16x16x32_bf16 v[28:31], v[238:241], v[174:177], v[28:31]
	v_mfma_f32_16x16x32_bf16 v[24:27], v[238:241], v[178:181], v[24:27]
	v_mfma_f32_16x16x32_bf16 v[20:23], v[238:241], v[182:185], v[20:23]
	v_mfma_f32_16x16x32_bf16 v[16:19], v[238:241], v[186:189], v[16:19]
	ds_read_b128 v[230:233], v158 offset:1024
	s_waitcnt lgkmcnt(9)
	v_mfma_f32_16x16x32_bf16 v[12:15], v[242:245], v[174:177], v[12:15]
	v_mfma_f32_16x16x32_bf16 v[8:11], v[242:245], v[178:181], v[8:11]
	v_mfma_f32_16x16x32_bf16 v[4:7], v[242:245], v[182:185], v[4:7]
	v_mfma_f32_16x16x32_bf16 v[0:3], v[242:245], v[186:189], v[0:3]
	ds_read_b128 v[234:237], v159 offset:1024
	s_waitcnt lgkmcnt(3)
	v_mfma_f32_16x16x32_bf16 v[124:127], v[214:217], v[190:193], v[124:127]
	v_mfma_f32_16x16x32_bf16 v[120:123], v[214:217], v[194:197], v[120:123]
	v_mfma_f32_16x16x32_bf16 v[116:119], v[214:217], v[198:201], v[116:119]
	v_mfma_f32_16x16x32_bf16 v[112:115], v[214:217], v[210:213], v[112:115]
	ds_read_b128 v[238:241], v160 offset:1024
	v_mfma_f32_16x16x32_bf16 v[108:111], v[218:221], v[190:193], v[108:111]
	v_mfma_f32_16x16x32_bf16 v[104:107], v[218:221], v[194:197], v[104:107]
	v_mfma_f32_16x16x32_bf16 v[100:103], v[218:221], v[198:201], v[100:103]
	v_mfma_f32_16x16x32_bf16 v[96:99], v[218:221], v[210:213], v[96:99]
	ds_read_b128 v[242:245], v161 offset:1024
	v_mfma_f32_16x16x32_bf16 v[92:95], v[222:225], v[190:193], v[92:95]
	v_mfma_f32_16x16x32_bf16 v[88:91], v[222:225], v[194:197], v[88:91]
	v_mfma_f32_16x16x32_bf16 v[84:87], v[222:225], v[198:201], v[84:87]
	v_mfma_f32_16x16x32_bf16 v[80:83], v[222:225], v[210:213], v[80:83]
	s_waitcnt lgkmcnt(4)
	v_mfma_f32_16x16x32_bf16 v[76:79], v[226:229], v[190:193], v[76:79]
	v_mfma_f32_16x16x32_bf16 v[72:75], v[226:229], v[194:197], v[72:75]
	v_mfma_f32_16x16x32_bf16 v[68:71], v[226:229], v[198:201], v[68:71]
	v_mfma_f32_16x16x32_bf16 v[64:67], v[226:229], v[210:213], v[64:67]
	s_waitcnt lgkmcnt(3)
	v_mfma_f32_16x16x32_bf16 v[60:63], v[230:233], v[190:193], v[60:63]
	v_mfma_f32_16x16x32_bf16 v[56:59], v[230:233], v[194:197], v[56:59]
	v_mfma_f32_16x16x32_bf16 v[52:55], v[230:233], v[198:201], v[52:55]
	v_mfma_f32_16x16x32_bf16 v[48:51], v[230:233], v[210:213], v[48:51]
	s_waitcnt lgkmcnt(0)
	s_waitcnt vmcnt(0)
	s_barrier
	ds_read_b128 v[174:177], v162 offset:32768
	ds_read_b128 v[178:181], v162 offset:34816
	ds_read_b128 v[182:185], v162 offset:36864
	ds_read_b128 v[186:189], v162 offset:38912
	ds_read_b128 v[214:217], v170
	ds_read_b128 v[218:221], v171
	ds_read_b128 v[222:225], v163
	s_cmp_gt_u32 s23, 13
	s_cbranch_scc1 .Lg1_nostage0
	s_add_u32 m0, s24, 0x0
	v_mfma_f32_16x16x32_bf16 v[44:47], v[234:237], v[190:193], v[44:47]
	global_load_lds_dwordx4 v246, s[98:99]
	s_add_u32 m0, s24, 0x8000
	v_mfma_f32_16x16x32_bf16 v[40:43], v[234:237], v[194:197], v[40:43]
	global_load_lds_dwordx4 v246, s[100:101]
	s_add_u32 m0, s24, 0x2000
	v_mfma_f32_16x16x32_bf16 v[36:39], v[234:237], v[198:201], v[36:39]
	global_load_lds_dwordx4 v247, s[98:99]
	s_add_u32 m0, s24, 0xa000
	v_mfma_f32_16x16x32_bf16 v[32:35], v[234:237], v[210:213], v[32:35]
	global_load_lds_dwordx4 v247, s[100:101]
	s_add_u32 m0, s24, 0x4000
	v_mfma_f32_16x16x32_bf16 v[28:31], v[238:241], v[190:193], v[28:31]
	global_load_lds_dwordx4 v248, s[98:99]
	s_add_u32 m0, s24, 0xc000
	v_mfma_f32_16x16x32_bf16 v[24:27], v[238:241], v[194:197], v[24:27]
	global_load_lds_dwordx4 v248, s[100:101]
	s_add_u32 m0, s24, 0x6000
	v_mfma_f32_16x16x32_bf16 v[20:23], v[238:241], v[198:201], v[20:23]
	global_load_lds_dwordx4 v249, s[98:99]
	s_add_u32 m0, s24, 0xe000
	v_mfma_f32_16x16x32_bf16 v[16:19], v[238:241], v[210:213], v[16:19]
	global_load_lds_dwordx4 v249, s[100:101]
	v_mfma_f32_16x16x32_bf16 v[12:15], v[242:245], v[190:193], v[12:15]
	v_mfma_f32_16x16x32_bf16 v[8:11], v[242:245], v[194:197], v[8:11]
	v_mfma_f32_16x16x32_bf16 v[4:7], v[242:245], v[198:201], v[4:7]
	v_mfma_f32_16x16x32_bf16 v[0:3], v[242:245], v[210:213], v[0:3]
	s_add_u32 s98, s98, 0x80
	s_addc_u32 s99, s99, 0
	s_add_u32 s100, s100, 0x80
	s_addc_u32 s101, s101, 0
	s_branch .Lg1_half1
.Lg1_nostage0:
	v_mfma_f32_16x16x32_bf16 v[44:47], v[234:237], v[190:193], v[44:47]
	v_mfma_f32_16x16x32_bf16 v[40:43], v[234:237], v[194:197], v[40:43]
	v_mfma_f32_16x16x32_bf16 v[36:39], v[234:237], v[198:201], v[36:39]
	v_mfma_f32_16x16x32_bf16 v[32:35], v[234:237], v[210:213], v[32:35]
	v_mfma_f32_16x16x32_bf16 v[28:31], v[238:241], v[190:193], v[28:31]
	v_mfma_f32_16x16x32_bf16 v[24:27], v[238:241], v[194:197], v[24:27]
	v_mfma_f32_16x16x32_bf16 v[20:23], v[238:241], v[198:201], v[20:23]
	v_mfma_f32_16x16x32_bf16 v[16:19], v[238:241], v[210:213], v[16:19]
	v_mfma_f32_16x16x32_bf16 v[12:15], v[242:245], v[190:193], v[12:15]
	v_mfma_f32_16x16x32_bf16 v[8:11], v[242:245], v[194:197], v[8:11]
	v_mfma_f32_16x16x32_bf16 v[4:7], v[242:245], v[198:201], v[4:7]
	v_mfma_f32_16x16x32_bf16 v[0:3], v[242:245], v[210:213], v[0:3]
.Lg1_half1:
	ds_read_b128 v[226:229], v164
	ds_read_b128 v[230:233], v165
	ds_read_b128 v[234:237], v166
	s_waitcnt lgkmcnt(5)
	v_mfma_f32_16x16x32_bf16 v[124:127], v[214:217], v[174:177], v[124:127]
	v_mfma_f32_16x16x32_bf16 v[120:123], v[214:217], v[178:181], v[120:123]
	v_mfma_f32_16x16x32_bf16 v[116:119], v[214:217], v[182:185], v[116:119]
	v_mfma_f32_16x16x32_bf16 v[112:115], v[214:217], v[186:189], v[112:115]
	ds_read_b128 v[238:241], v167
	s_waitcnt lgkmcnt(5)
	v_mfma_f32_16x16x32_bf16 v[108:111], v[218:221], v[174:177], v[108:111]
	v_mfma_f32_16x16x32_bf16 v[104:107], v[218:221], v[178:181], v[104:107]
	v_mfma_f32_16x16x32_bf16 v[100:103], v[218:221], v[182:185], v[100:103]
	v_mfma_f32_16x16x32_bf16 v[96:99], v[218:221], v[186:189], v[96:99]
	ds_read_b128 v[242:245], v168
	ds_read_b128 v[190:193], v162 offset:33792
	s_waitcnt lgkmcnt(6)
	v_mfma_f32_16x16x32_bf16 v[92:95], v[222:225], v[174:177], v[92:95]
	v_mfma_f32_16x16x32_bf16 v[88:91], v[222:225], v[178:181], v[88:91]
	v_mfma_f32_16x16x32_bf16 v[84:87], v[222:225], v[182:185], v[84:87]
	v_mfma_f32_16x16x32_bf16 v[80:83], v[222:225], v[186:189], v[80:83]
	ds_read_b128 v[214:217], v170 offset:1024
	ds_read_b128 v[194:197], v162 offset:35840
	s_waitcnt lgkmcnt(7)
	v_mfma_f32_16x16x32_bf16 v[76:79], v[226:229], v[174:177], v[76:79]
	v_mfma_f32_16x16x32_bf16 v[72:75], v[226:229], v[178:181], v[72:75]
	v_mfma_f32_16x16x32_bf16 v[68:71], v[226:229], v[182:185], v[68:71]
	v_mfma_f32_16x16x32_bf16 v[64:67], v[226:229], v[186:189], v[64:67]
	ds_read_b128 v[218:221], v171 offset:1024
	ds_read_b128 v[198:201], v162 offset:37888
	s_waitcnt lgkmcnt(8)
	v_mfma_f32_16x16x32_bf16 v[60:63], v[230:233], v[174:177], v[60:63]
	v_mfma_f32_16x16x32_bf16 v[56:59], v[230:233], v[178:181], v[56:59]
	v_mfma_f32_16x16x32_bf16 v[52:55], v[230:233], v[182:185], v[52:55]
	v_mfma_f32_16x16x32_bf16 v[48:51], v[230:233], v[186:189], v[48:51]
	ds_read_b128 v[222:225], v163 offset:1024
	ds_read_b128 v[210:213], v162 offset:39936
	s_waitcnt lgkmcnt(9)
	v_mfma_f32_16x16x32_bf16 v[44:47], v[234:237], v[174:177], v[44:47]
	v_mfma_f32_16x16x32_bf16 v[40:43], v[234:237], v[178:181], v[40:43]
	v_mfma_f32_16x16x32_bf16 v[36:39], v[234:237], v[182:185], v[36:39]
	v_mfma_f32_16x16x32_bf16 v[32:35], v[234:237], v[186:189], v[32:35]
	ds_read_b128 v[226:229], v164 offset:1024
	s_waitcnt lgkmcnt(9)
	v_mfma_f32_16x16x32_bf16 v[28:31], v[238:241], v[174:177], v[28:31]
	v_mfma_f32_16x16x32_bf16 v[24:27], v[238:241], v[178:181], v[24:27]
	v_mfma_f32_16x16x32_bf16 v[20:23], v[238:241], v[182:185], v[20:23]
	v_mfma_f32_16x16x32_bf16 v[16:19], v[238:241], v[186:189], v[16:19]
	ds_read_b128 v[230:233], v165 offset:1024
	s_waitcnt lgkmcnt(9)
	v_mfma_f32_16x16x32_bf16 v[12:15], v[242:245], v[174:177], v[12:15]
	v_mfma_f32_16x16x32_bf16 v[8:11], v[242:245], v[178:181], v[8:11]
	v_mfma_f32_16x16x32_bf16 v[4:7], v[242:245], v[182:185], v[4:7]
	v_mfma_f32_16x16x32_bf16 v[0:3], v[242:245], v[186:189], v[0:3]
	ds_read_b128 v[234:237], v166 offset:1024
	s_waitcnt lgkmcnt(3)
	v_mfma_f32_16x16x32_bf16 v[124:127], v[214:217], v[190:193], v[124:127]
	v_mfma_f32_16x16x32_bf16 v[120:123], v[214:217], v[194:197], v[120:123]
	v_mfma_f32_16x16x32_bf16 v[116:119], v[214:217], v[198:201], v[116:119]
	v_mfma_f32_16x16x32_bf16 v[112:115], v[214:217], v[210:213], v[112:115]
	ds_read_b128 v[238:241], v167 offset:1024
	v_mfma_f32_16x16x32_bf16 v[108:111], v[218:221], v[190:193], v[108:111]
	v_mfma_f32_16x16x32_bf16 v[104:107], v[218:221], v[194:197], v[104:107]
	v_mfma_f32_16x16x32_bf16 v[100:103], v[218:221], v[198:201], v[100:103]
	v_mfma_f32_16x16x32_bf16 v[96:99], v[218:221], v[210:213], v[96:99]
	ds_read_b128 v[242:245], v168 offset:1024
	v_mfma_f32_16x16x32_bf16 v[92:95], v[222:225], v[190:193], v[92:95]
	v_mfma_f32_16x16x32_bf16 v[88:91], v[222:225], v[194:197], v[88:91]
	v_mfma_f32_16x16x32_bf16 v[84:87], v[222:225], v[198:201], v[84:87]
	v_mfma_f32_16x16x32_bf16 v[80:83], v[222:225], v[210:213], v[80:83]
	s_waitcnt lgkmcnt(4)
	v_mfma_f32_16x16x32_bf16 v[76:79], v[226:229], v[190:193], v[76:79]
	v_mfma_f32_16x16x32_bf16 v[72:75], v[226:229], v[194:197], v[72:75]
	v_mfma_f32_16x16x32_bf16 v[68:71], v[226:229], v[198:201], v[68:71]
	v_mfma_f32_16x16x32_bf16 v[64:67], v[226:229], v[210:213], v[64:67]
	s_waitcnt lgkmcnt(3)
	v_mfma_f32_16x16x32_bf16 v[60:63], v[230:233], v[190:193], v[60:63]
	v_mfma_f32_16x16x32_bf16 v[56:59], v[230:233], v[194:197], v[56:59]
	v_mfma_f32_16x16x32_bf16 v[52:55], v[230:233], v[198:201], v[52:55]
	v_mfma_f32_16x16x32_bf16 v[48:51], v[230:233], v[210:213], v[48:51]
	s_waitcnt lgkmcnt(0)
	s_waitcnt vmcnt(0)
	s_barrier
	s_cmp_gt_u32 s23, 13
	s_cbranch_scc1 .Lg1_last
	ds_read_b128 v[174:177], v153 offset:32768
	ds_read_b128 v[178:181], v153 offset:34816
	ds_read_b128 v[182:185], v153 offset:36864
	ds_read_b128 v[186:189], v153 offset:38912
	ds_read_b128 v[214:217], v154
	ds_read_b128 v[218:221], v155
	ds_read_b128 v[222:225], v156
	s_add_u32 m0, s24, 0x10400
	v_mfma_f32_16x16x32_bf16 v[44:47], v[234:237], v[190:193], v[44:47]
	global_load_lds_dwordx4 v246, s[98:99]
	s_add_u32 m0, s24, 0x18400
	v_mfma_f32_16x16x32_bf16 v[40:43], v[234:237], v[194:197], v[40:43]
	global_load_lds_dwordx4 v246, s[100:101]
	s_add_u32 m0, s24, 0x12400
	v_mfma_f32_16x16x32_bf16 v[36:39], v[234:237], v[198:201], v[36:39]
	global_load_lds_dwordx4 v247, s[98:99]
	s_add_u32 m0, s24, 0x1a400
	v_mfma_f32_16x16x32_bf16 v[32:35], v[234:237], v[210:213], v[32:35]
	global_load_lds_dwordx4 v247, s[100:101]
	s_add_u32 m0, s24, 0x14400
	v_mfma_f32_16x16x32_bf16 v[28:31], v[238:241], v[190:193], v[28:31]
	global_load_lds_dwordx4 v248, s[98:99]
	s_add_u32 m0, s24, 0x1c400
	v_mfma_f32_16x16x32_bf16 v[24:27], v[238:241], v[194:197], v[24:27]
	global_load_lds_dwordx4 v248, s[100:101]
	s_add_u32 m0, s24, 0x16400
	v_mfma_f32_16x16x32_bf16 v[20:23], v[238:241], v[198:201], v[20:23]
	global_load_lds_dwordx4 v249, s[98:99]
	s_add_u32 m0, s24, 0x1e400
	v_mfma_f32_16x16x32_bf16 v[16:19], v[238:241], v[210:213], v[16:19]
	global_load_lds_dwordx4 v249, s[100:101]
	v_mfma_f32_16x16x32_bf16 v[12:15], v[242:245], v[190:193], v[12:15]
	v_mfma_f32_16x16x32_bf16 v[8:11], v[242:245], v[194:197], v[8:11]
	v_mfma_f32_16x16x32_bf16 v[4:7], v[242:245], v[198:201], v[4:7]
	v_mfma_f32_16x16x32_bf16 v[0:3], v[242:245], v[210:213], v[0:3]
	s_add_u32 s98, s98, 0x80
	s_addc_u32 s99, s99, 0
	s_add_u32 s100, s100, 0x80
	s_addc_u32 s101, s101, 0
	s_add_i32 s23, s23, 2
	s_branch .LBB0_203
.Lg1_last:
	v_mfma_f32_16x16x32_bf16 v[44:47], v[234:237], v[190:193], v[44:47]
	v_mfma_f32_16x16x32_bf16 v[40:43], v[234:237], v[194:197], v[40:43]
	v_mfma_f32_16x16x32_bf16 v[36:39], v[234:237], v[198:201], v[36:39]
	v_mfma_f32_16x16x32_bf16 v[32:35], v[234:237], v[210:213], v[32:35]
	v_mfma_f32_16x16x32_bf16 v[28:31], v[238:241], v[190:193], v[28:31]
	v_mfma_f32_16x16x32_bf16 v[24:27], v[238:241], v[194:197], v[24:27]
	v_mfma_f32_16x16x32_bf16 v[20:23], v[238:241], v[198:201], v[20:23]
	v_mfma_f32_16x16x32_bf16 v[16:19], v[238:241], v[210:213], v[16:19]
	v_mfma_f32_16x16x32_bf16 v[12:15], v[242:245], v[190:193], v[12:15]
	v_mfma_f32_16x16x32_bf16 v[8:11], v[242:245], v[194:197], v[8:11]
	v_mfma_f32_16x16x32_bf16 v[4:7], v[242:245], v[198:201], v[4:7]
	v_mfma_f32_16x16x32_bf16 v[0:3], v[242:245], v[210:213], v[0:3]
	s_nop 15
	s_nop 15

.LBB0_1675:
	v_max3_f32 v70, v0, s80, v1
	v_max3_f32 v70, v70, v2, v3
	v_max3_f32 v70, v70, v4, v5
	v_max3_f32 v70, v70, v6, v7
	v_max3_f32 v70, v70, v8, v9
	v_max3_f32 v70, v70, v10, v11
	v_cmp_lt_i32_e32 vcc, v87, v88
	v_max3_f32 v70, v70, v12, v13
	v_max3_f32 v70, v70, v14, v15
	v_cndmask_b32_e32 v71, v133, v87, vcc
	v_lshlrev_b32_e32 v71, 2, v71
	ds_bpermute_b32 v71, v71, v70
	v_cmp_lt_i32_e32 vcc, v89, v88
	s_waitcnt lgkmcnt(0)
	v_max_f32_e32 v71, v71, v71
	v_max_f32_e32 v70, v70, v71
	v_cndmask_b32_e32 v71, v133, v89, vcc
	v_lshlrev_b32_e32 v71, 2, v71
	ds_bpermute_b32 v71, v71, v70
	s_waitcnt lgkmcnt(0)
	v_max3_f32 v71, v92, v70, v71
	v_cmp_neq_f32_e32 vcc, s80, v71
	s_nop 1
	v_cndmask_b32_e32 v100, 0, v71, vcc
	v_sub_f32_e32 v0, v0, v100
	v_sub_f32_e32 v1, v1, v100
	v_sub_f32_e32 v70, v92, v100
	v_exp_f32_e32 v92, v0
	v_exp_f32_e32 v93, v1
	v_sub_f32_e32 v0, v2, v100
	v_exp_f32_e32 v94, v0
	v_sub_f32_e32 v0, v3, v100
	v_exp_f32_e32 v95, v0
	v_sub_f32_e32 v1, v4, v100
	v_add_f32_e32 v0, 0, v92
	v_exp_f32_e32 v96, v1
	v_sub_f32_e32 v1, v5, v100
	v_add_f32_e32 v0, v93, v0
	v_exp_f32_e32 v97, v1
	v_sub_f32_e32 v1, v6, v100
	v_add_f32_e32 v0, v94, v0
	v_exp_f32_e32 v98, v1
	v_sub_f32_e32 v1, v7, v100
	v_add_f32_e32 v0, v95, v0
	v_exp_f32_e32 v7, v1
	v_add_f32_e32 v0, v96, v0
	v_add_f32_e32 v0, v97, v0
	v_add_f32_e32 v0, v98, v0
	v_add_f32_e32 v101, v7, v0
	v_sub_f32_e32 v0, v8, v100
	v_exp_f32_e32 v102, v0
	v_sub_f32_e32 v0, v9, v100
	v_exp_f32_e32 v103, v0
	v_sub_f32_e32 v0, v10, v100
	v_exp_f32_e32 v70, v70
	v_exp_f32_e32 v104, v0
	v_sub_f32_e32 v0, v11, v100
	v_exp_f32_e32 v105, v0
	v_sub_f32_e32 v0, v12, v100
	v_exp_f32_e32 v106, v0
	v_sub_f32_e32 v0, v13, v100
	v_exp_f32_e32 v107, v0
	v_pk_mul_f32 v[2:3], v[54:55], v[70:71] op_sel_hi:[1,0]
	v_pk_mul_f32 v[0:1], v[52:53], v[70:71] op_sel_hi:[1,0]
	v_cvt_pk_bf16_f32 v4, v92, v93
	v_cvt_pk_bf16_f32 v5, v94, v95
	v_cvt_pk_bf16_f32 v6, v96, v97
	v_cvt_pk_bf16_f32 v7, v98, v7
	ds_read_b64_tr_b16 v[96:97], v74 offset:32768
	ds_read_b64_tr_b16 v[92:93], v74 offset:32800
	ds_read_b64_tr_b16 v[52:53], v74 offset:32832
	ds_read_b64_tr_b16 v[8:9], v74 offset:32864
	ds_read_b64_tr_b16 v[98:99], v74 offset:35328
	ds_read_b64_tr_b16 v[94:95], v74 offset:35360
	ds_read_b64_tr_b16 v[54:55], v74 offset:35392
	ds_read_b64_tr_b16 v[10:11], v74 offset:35424
	s_waitcnt lgkmcnt(0)
	v_sub_f32_e32 v12, v14, v100
	s_nop 0
	v_mfma_f32_16x16x32_bf16 v[0:3], v[96:99], v[4:7], v[0:3]
	v_mul_f32_e64 v50, v50, v70
	v_mul_f32_e64 v51, v51, v70
	v_pk_mul_f32 v[48:49], v[48:49], v[70:71] op_sel_hi:[1,0]
	v_exp_f32_e32 v96, v12
	v_pk_mul_f32 v[12:13], v[44:45], v[70:71] op_sel_hi:[1,0]
	v_mfma_f32_16x16x32_bf16 v[48:51], v[92:95], v[4:7], v[48:51]
	v_sub_f32_e32 v92, v15, v100
	v_pk_mul_f32 v[14:15], v[46:47], v[70:71] op_sel_hi:[1,0]
	v_pk_mul_f32 v[26:27], v[26:27], v[70:71] op_sel_hi:[1,0]
	v_pk_mul_f32 v[24:25], v[24:25], v[70:71] op_sel_hi:[1,0]
	v_mfma_f32_16x16x32_bf16 v[12:15], v[52:55], v[4:7], v[12:15]
	v_exp_f32_e32 v97, v92
	v_mfma_f32_16x16x32_bf16 v[4:7], v[8:11], v[4:7], v[24:27]
	ds_read_b64_tr_b16 v[52:53], v82 offset:32768
	ds_read_b64_tr_b16 v[92:93], v82 offset:32800
	ds_read_b64_tr_b16 v[44:45], v82 offset:32832
	ds_read_b64_tr_b16 v[24:25], v82 offset:32864
	ds_read_b64_tr_b16 v[54:55], v82 offset:35328
	ds_read_b64_tr_b16 v[94:95], v82 offset:35360
	ds_read_b64_tr_b16 v[46:47], v82 offset:35392
	ds_read_b64_tr_b16 v[26:27], v82 offset:35424
	s_waitcnt lgkmcnt(0)
	v_cvt_pk_bf16_f32 v8, v102, v103
	v_cvt_pk_bf16_f32 v9, v104, v105
	v_cvt_pk_bf16_f32 v10, v106, v107
	v_cvt_pk_bf16_f32 v11, v96, v97
	s_nop 0
	v_mfma_f32_16x16x32_bf16 v[52:55], v[52:55], v[8:11], v[0:3]
	s_nop 2
	v_add_f32_e32 v0, v102, v101
	v_add_f32_e32 v0, v103, v0
	v_add_f32_e32 v0, v104, v0
	v_add_f32_e32 v0, v105, v0
	v_add_f32_e32 v0, v106, v0
	v_add_f32_e32 v0, v107, v0
	v_mfma_f32_16x16x32_bf16 v[48:51], v[92:95], v[8:11], v[48:51]
	v_add_f32_e32 v0, v96, v0
	v_add_f32_e32 v0, v97, v0
	v_fmac_f32_e32 v0, v83, v70
	v_mfma_f32_16x16x32_bf16 v[44:47], v[44:47], v[8:11], v[12:15]
	v_mov_b32_e32 v83, v0
	v_mov_b32_e32 v92, v71
	v_mfma_f32_16x16x32_bf16 v[24:27], v[24:27], v[8:11], v[4:7]

.LBB0_1678:
	s_add_i32 s91, s88, -1
	s_cmp_lt_u32 s91, s85
	s_cselect_b64 s[62:63], -1, 0
	s_cmp_ge_u32 s91, s85
	s_waitcnt vmcnt(4)
	ds_write_b128 v58, v[28:31]
	s_waitcnt vmcnt(3)
	ds_write_b128 v58, v[32:35] offset:10240
	s_waitcnt lgkmcnt(0)
	s_barrier
	s_cbranch_scc1 .Lp3a_noload
	v_add_u32_e32 v0, s90, v57
	v_add_u32_e32 v0, 0x80, v0
	v_min_i32_e32 v2, s87, v0
	v_mad_i64_i32 v[0:1], s[0:1], v2, s71, v[60:61]
	global_load_dwordx4 v[28:31], v[0:1], off
	v_mad_i64_i32 v[0:1], s[0:1], v2, s71, v[62:63]
	global_load_dwordx4 v[32:35], v[0:1], off

.LBB0_1686:
	s_or_b64 exec, exec, s[66:67]
	s_andn2_b64 vcc, exec, s[64:65]
	s_cbranch_vccnz .LBB0_1690
	s_cmp_ge_u32 s88, s85
	ds_write_b128 v58, v[36:39] offset:32768
	ds_write_b128 v58, v[40:43] offset:43008
	s_waitcnt lgkmcnt(0)
	s_barrier
	s_cbranch_scc0 .LBB0_1691
	s_andn2_b64 vcc, exec, s[62:63]
	s_waitcnt vmcnt(0)
	v_mov_b64_e32 v[68:69], v[70:71]
	s_cbranch_vccz .LBB0_1692

.LBB0_1693:
	ds_read_b128 v[0:3], v64 offset:32768
	ds_read_b128 v[4:7], v64 offset:32832
	ds_read_b128 v[8:11], v64 offset:35328
	ds_read_b128 v[12:15], v64 offset:35392
	ds_read_b128 v[94:97], v64 offset:37888
	ds_read_b128 v[98:101], v64 offset:37952
	v_and_b32_e32 v93, v70, v59
	s_waitcnt lgkmcnt(5)
	v_mfma_f32_16x16x32_bf16 v[0:3], v[0:3], v[16:19], 0
	v_and_b32_e32 v106, v70, v75
	v_cmp_ne_u32_e32 vcc, 0, v93
	v_and_b32_e32 v93, v70, v76
	s_waitcnt lgkmcnt(3)
	v_mfma_f32_16x16x32_bf16 v[8:11], v[8:11], v[16:19], 0
	s_add_i32 s0, s90, 64
	s_cmp_le_u32 s0, s89
	v_mfma_f32_16x16x32_bf16 v[0:3], v[4:7], v[20:23], v[0:3]
	ds_read_b128 v[4:7], v64 offset:40448
	ds_read_b128 v[102:105], v64 offset:40512
	s_waitcnt lgkmcnt(4)
	v_mfma_f32_16x16x32_bf16 v[8:11], v[12:15], v[20:23], v[8:11]
	s_nop 3
	v_cndmask_b32_e32 v0, v86, v0, vcc
	v_cmp_ne_u32_e32 vcc, 0, v106
	s_waitcnt lgkmcnt(3)
	v_mfma_f32_16x16x32_bf16 v[12:15], v[94:97], v[16:19], 0
	v_cndmask_b32_e32 v1, v86, v1, vcc
	v_cmp_ne_u32_e32 vcc, 0, v93
	v_and_b32_e32 v93, v70, v77
	s_waitcnt lgkmcnt(1)
	v_mfma_f32_16x16x32_bf16 v[94:97], v[4:7], v[16:19], 0
	v_cndmask_b32_e32 v2, v86, v2, vcc
	v_cmp_ne_u32_e32 vcc, 0, v93
	v_and_b32_e32 v4, v70, v78
	v_and_b32_e32 v5, v70, v79
	v_cndmask_b32_e32 v3, v86, v3, vcc
	v_cmp_ne_u32_e32 vcc, 0, v4
	v_mfma_f32_16x16x32_bf16 v[12:15], v[98:101], v[20:23], v[12:15]
	v_and_b32_e32 v6, v70, v80
	v_cndmask_b32_e32 v4, v86, v8, vcc
	v_cmp_ne_u32_e32 vcc, 0, v5
	v_and_b32_e32 v7, v70, v81
	v_and_b32_e32 v8, v71, v59
	v_cndmask_b32_e32 v5, v86, v9, vcc
	v_cmp_ne_u32_e32 vcc, 0, v6
	v_and_b32_e32 v9, v71, v75
	s_waitcnt lgkmcnt(0)
	v_mfma_f32_16x16x32_bf16 v[94:97], v[102:105], v[20:23], v[94:97]
	v_cndmask_b32_e32 v6, v86, v10, vcc
	v_cmp_ne_u32_e32 vcc, 0, v7
	v_and_b32_e32 v10, v71, v76
	s_nop 0
	v_cndmask_b32_e32 v7, v86, v11, vcc
	v_cmp_ne_u32_e32 vcc, 0, v8
	v_and_b32_e32 v11, v71, v77
	s_nop 0
	v_cndmask_b32_e32 v8, v86, v12, vcc
	v_cmp_ne_u32_e32 vcc, 0, v9
	v_and_b32_e32 v12, v71, v78
	s_nop 0
	v_cndmask_b32_e32 v9, v86, v13, vcc
	v_cmp_ne_u32_e32 vcc, 0, v10
	v_and_b32_e32 v13, v71, v79
	s_nop 0
	v_cndmask_b32_e32 v10, v86, v14, vcc
	v_cmp_ne_u32_e32 vcc, 0, v11
	v_and_b32_e32 v14, v71, v80
	v_cmp_ne_u32_e64 s[0:1], 0, v14
	v_cndmask_b32_e32 v11, v86, v15, vcc
	v_cmp_ne_u32_e32 vcc, 0, v12
	v_and_b32_e32 v15, v71, v81
	v_cndmask_b32_e64 v14, v86, v96, s[0:1]
	v_cndmask_b32_e32 v12, v86, v94, vcc
	v_cmp_ne_u32_e32 vcc, 0, v13
	s_nop 1
	v_cndmask_b32_e32 v13, v86, v95, vcc
	v_cmp_ne_u32_e32 vcc, 0, v15
	s_nop 1
	v_cndmask_b32_e32 v15, v86, v97, vcc
	s_cbranch_scc1 .LBB0_1675
	v_add_u32_e32 v70, s90, v72
	v_add_u32_e32 v71, 64, v70
	v_cmp_gt_u32_e32 vcc, s86, v71
	v_add_u32_e32 v71, 0x41, v70
	s_nop 0
	v_cndmask_b32_e32 v0, v86, v0, vcc
	v_cmp_gt_u32_e32 vcc, s86, v71
	v_add_u32_e32 v71, 0x42, v70
	s_nop 0
	v_cndmask_b32_e32 v1, v86, v1, vcc
	v_cmp_gt_u32_e32 vcc, s86, v71
	v_add_u32_e32 v71, 0x43, v70
	s_nop 0
	v_cndmask_b32_e32 v2, v86, v2, vcc
	v_cmp_gt_u32_e32 vcc, s86, v71
	v_add_u32_e32 v71, 0x50, v70
	v_cmp_gt_u32_e64 s[0:1], s86, v71
	v_add_u32_e32 v71, 0x51, v70
	v_cmp_gt_u32_e64 s[2:3], s86, v71
	v_add_u32_e32 v71, 0x52, v70
	v_cmp_gt_u32_e64 s[4:5], s86, v71
	v_add_u32_e32 v71, 0x53, v70
	v_cmp_gt_u32_e64 s[6:7], s86, v71
	v_add_u32_e32 v71, 0x60, v70
	v_cmp_gt_u32_e64 s[12:13], s86, v71
	v_add_u32_e32 v71, 0x61, v70
	v_cmp_gt_u32_e64 s[14:15], s86, v71
	v_add_u32_e32 v71, 0x62, v70
	v_cmp_gt_u32_e64 s[16:17], s86, v71
	v_add_u32_e32 v71, 0x63, v70
	v_cmp_gt_u32_e64 s[18:19], s86, v71
	v_add_u32_e32 v71, 0x70, v70
	v_cmp_gt_u32_e64 s[20:21], s86, v71
	v_add_u32_e32 v71, 0x71, v70
	v_cmp_gt_u32_e64 s[22:23], s86, v71
	v_add_u32_e32 v71, 0x72, v70
	v_add_u32_e32 v70, 0x73, v70
	v_cmp_gt_u32_e64 s[24:25], s86, v71
	v_cmp_gt_u32_e64 s[26:27], s86, v70
	s_or_b64 s[24:25], s[26:27], s[24:25]
	s_or_b64 s[22:23], s[24:25], s[22:23]
	s_or_b64 s[20:21], s[22:23], s[20:21]
	s_or_b64 s[18:19], s[20:21], s[18:19]
	s_or_b64 s[16:17], s[18:19], s[16:17]
	s_or_b64 s[14:15], s[16:17], s[14:15]
	s_or_b64 s[12:13], s[14:15], s[12:13]
	s_or_b64 s[6:7], s[12:13], s[6:7]
	s_or_b64 s[4:5], s[6:7], s[4:5]
	s_or_b64 s[2:3], s[4:5], s[2:3]
	s_or_b64 s[0:1], s[2:3], s[0:1]
	s_or_b64 vcc, s[0:1], vcc
	v_cndmask_b32_e64 v14, v86, v14, s[24:25]
	v_cndmask_b32_e64 v13, v86, v13, s[22:23]
	v_cndmask_b32_e64 v12, v86, v12, s[20:21]
	v_cndmask_b32_e64 v11, v86, v11, s[18:19]
	v_cndmask_b32_e64 v10, v86, v10, s[16:17]
	v_cndmask_b32_e64 v9, v86, v9, s[14:15]
	v_cndmask_b32_e64 v8, v86, v8, s[12:13]
	v_cndmask_b32_e64 v7, v86, v7, s[6:7]
	v_cndmask_b32_e64 v6, v86, v6, s[4:5]
	v_cndmask_b32_e64 v5, v86, v5, s[2:3]
	v_cndmask_b32_e64 v4, v86, v4, s[0:1]
	v_cndmask_b32_e32 v3, v86, v3, vcc
	v_cndmask_b32_e64 v15, v86, v15, s[26:27]
	s_branch .LBB0_1675

.LBB0_1788:
	ds_read_b128 v[222:225], v159
	ds_read_b128 v[226:229], v160
	ds_read_b128 v[230:233], v161
	s_waitcnt lgkmcnt(5)
	v_mfma_f32_16x16x32_bf16 v[124:127], v[210:213], v[178:181], v[124:127]
	v_mfma_f32_16x16x32_bf16 v[120:123], v[210:213], v[182:185], v[120:123]
	v_mfma_f32_16x16x32_bf16 v[116:119], v[210:213], v[186:189], v[116:119]
	v_mfma_f32_16x16x32_bf16 v[112:115], v[210:213], v[190:193], v[112:115]
	ds_read_b128 v[234:237], v162
	s_waitcnt lgkmcnt(5)
	v_mfma_f32_16x16x32_bf16 v[108:111], v[214:217], v[178:181], v[108:111]
	v_mfma_f32_16x16x32_bf16 v[104:107], v[214:217], v[182:185], v[104:107]
	v_mfma_f32_16x16x32_bf16 v[100:103], v[214:217], v[186:189], v[100:103]
	v_mfma_f32_16x16x32_bf16 v[96:99], v[214:217], v[190:193], v[96:99]
	ds_read_b128 v[238:241], v163
	ds_read_b128 v[194:197], v155 offset:33792
	s_waitcnt lgkmcnt(6)
	v_mfma_f32_16x16x32_bf16 v[92:95], v[218:221], v[178:181], v[92:95]
	v_mfma_f32_16x16x32_bf16 v[88:91], v[218:221], v[182:185], v[88:91]
	v_mfma_f32_16x16x32_bf16 v[84:87], v[218:221], v[186:189], v[84:87]
	v_mfma_f32_16x16x32_bf16 v[80:83], v[218:221], v[190:193], v[80:83]
	ds_read_b128 v[210:213], v156 offset:1024
	ds_read_b128 v[198:201], v155 offset:35840
	s_waitcnt lgkmcnt(7)
	v_mfma_f32_16x16x32_bf16 v[76:79], v[222:225], v[178:181], v[76:79]
	v_mfma_f32_16x16x32_bf16 v[72:75], v[222:225], v[182:185], v[72:75]
	v_mfma_f32_16x16x32_bf16 v[68:71], v[222:225], v[186:189], v[68:71]
	v_mfma_f32_16x16x32_bf16 v[64:67], v[222:225], v[190:193], v[64:67]
	ds_read_b128 v[214:217], v157 offset:1024
	ds_read_b128 v[202:205], v155 offset:37888
	s_waitcnt lgkmcnt(8)
	v_mfma_f32_16x16x32_bf16 v[60:63], v[226:229], v[178:181], v[60:63]
	v_mfma_f32_16x16x32_bf16 v[56:59], v[226:229], v[182:185], v[56:59]
	v_mfma_f32_16x16x32_bf16 v[52:55], v[226:229], v[186:189], v[52:55]
	v_mfma_f32_16x16x32_bf16 v[48:51], v[226:229], v[190:193], v[48:51]
	ds_read_b128 v[218:221], v158 offset:1024
	ds_read_b128 v[206:209], v155 offset:39936
	s_waitcnt lgkmcnt(9)
	v_mfma_f32_16x16x32_bf16 v[44:47], v[230:233], v[178:181], v[44:47]
	v_mfma_f32_16x16x32_bf16 v[40:43], v[230:233], v[182:185], v[40:43]
	v_mfma_f32_16x16x32_bf16 v[36:39], v[230:233], v[186:189], v[36:39]
	v_mfma_f32_16x16x32_bf16 v[32:35], v[230:233], v[190:193], v[32:35]
	ds_read_b128 v[222:225], v159 offset:1024
	s_waitcnt lgkmcnt(9)
	v_mfma_f32_16x16x32_bf16 v[28:31], v[234:237], v[178:181], v[28:31]
	v_mfma_f32_16x16x32_bf16 v[24:27], v[234:237], v[182:185], v[24:27]
	v_mfma_f32_16x16x32_bf16 v[20:23], v[234:237], v[186:189], v[20:23]
	v_mfma_f32_16x16x32_bf16 v[16:19], v[234:237], v[190:193], v[16:19]
	ds_read_b128 v[226:229], v160 offset:1024
	s_waitcnt lgkmcnt(9)
	v_mfma_f32_16x16x32_bf16 v[12:15], v[238:241], v[178:181], v[12:15]
	v_mfma_f32_16x16x32_bf16 v[8:11], v[238:241], v[182:185], v[8:11]
	v_mfma_f32_16x16x32_bf16 v[4:7], v[238:241], v[186:189], v[4:7]
	v_mfma_f32_16x16x32_bf16 v[0:3], v[238:241], v[190:193], v[0:3]
	ds_read_b128 v[230:233], v161 offset:1024
	s_waitcnt lgkmcnt(3)
	v_mfma_f32_16x16x32_bf16 v[124:127], v[210:213], v[194:197], v[124:127]
	v_mfma_f32_16x16x32_bf16 v[120:123], v[210:213], v[198:201], v[120:123]
	v_mfma_f32_16x16x32_bf16 v[116:119], v[210:213], v[202:205], v[116:119]
	v_mfma_f32_16x16x32_bf16 v[112:115], v[210:213], v[206:209], v[112:115]
	ds_read_b128 v[234:237], v162 offset:1024
	v_mfma_f32_16x16x32_bf16 v[108:111], v[214:217], v[194:197], v[108:111]
	v_mfma_f32_16x16x32_bf16 v[104:107], v[214:217], v[198:201], v[104:107]
	v_mfma_f32_16x16x32_bf16 v[100:103], v[214:217], v[202:205], v[100:103]
	v_mfma_f32_16x16x32_bf16 v[96:99], v[214:217], v[206:209], v[96:99]
	ds_read_b128 v[238:241], v163 offset:1024
	v_mfma_f32_16x16x32_bf16 v[92:95], v[218:221], v[194:197], v[92:95]
	v_mfma_f32_16x16x32_bf16 v[88:91], v[218:221], v[198:201], v[88:91]
	v_mfma_f32_16x16x32_bf16 v[84:87], v[218:221], v[202:205], v[84:87]
	v_mfma_f32_16x16x32_bf16 v[80:83], v[218:221], v[206:209], v[80:83]
	s_waitcnt lgkmcnt(4)
	v_mfma_f32_16x16x32_bf16 v[76:79], v[222:225], v[194:197], v[76:79]
	v_mfma_f32_16x16x32_bf16 v[72:75], v[222:225], v[198:201], v[72:75]
	v_mfma_f32_16x16x32_bf16 v[68:71], v[222:225], v[202:205], v[68:71]
	v_mfma_f32_16x16x32_bf16 v[64:67], v[222:225], v[206:209], v[64:67]
	s_waitcnt lgkmcnt(3)
	v_mfma_f32_16x16x32_bf16 v[60:63], v[226:229], v[194:197], v[60:63]
	v_mfma_f32_16x16x32_bf16 v[56:59], v[226:229], v[198:201], v[56:59]
	v_mfma_f32_16x16x32_bf16 v[52:55], v[226:229], v[202:205], v[52:55]
	v_mfma_f32_16x16x32_bf16 v[48:51], v[226:229], v[206:209], v[48:51]
	s_waitcnt lgkmcnt(0)
	s_waitcnt vmcnt(0)
	s_barrier
	ds_read_b128 v[178:181], v164 offset:32768
	ds_read_b128 v[182:185], v164 offset:34816
	ds_read_b128 v[186:189], v164 offset:36864
	ds_read_b128 v[190:193], v164 offset:38912
	ds_read_b128 v[210:213], v172
	ds_read_b128 v[214:217], v173
	ds_read_b128 v[218:221], v165
	s_cmp_gt_u32 s1, 13
	s_cbranch_scc1 .Lg4_nostage0
	s_add_u32 m0, s45, 0x0
	v_mfma_f32_16x16x32_bf16 v[44:47], v[230:233], v[194:197], v[44:47]
	global_load_lds_dwordx4 v174, s[98:99]
	s_add_u32 m0, s45, 0x8000
	v_mfma_f32_16x16x32_bf16 v[40:43], v[230:233], v[198:201], v[40:43]
	global_load_lds_dwordx4 v174, s[100:101]
	s_add_u32 m0, s45, 0x2000
	v_mfma_f32_16x16x32_bf16 v[36:39], v[230:233], v[202:205], v[36:39]
	global_load_lds_dwordx4 v175, s[98:99]
	s_add_u32 m0, s45, 0xa000
	v_mfma_f32_16x16x32_bf16 v[32:35], v[230:233], v[206:209], v[32:35]
	global_load_lds_dwordx4 v175, s[100:101]
	s_add_u32 m0, s45, 0x4000
	v_mfma_f32_16x16x32_bf16 v[28:31], v[234:237], v[194:197], v[28:31]
	global_load_lds_dwordx4 v176, s[98:99]
	s_add_u32 m0, s45, 0xc000
	v_mfma_f32_16x16x32_bf16 v[24:27], v[234:237], v[198:201], v[24:27]
	global_load_lds_dwordx4 v176, s[100:101]
	s_add_u32 m0, s45, 0x6000
	v_mfma_f32_16x16x32_bf16 v[20:23], v[234:237], v[202:205], v[20:23]
	global_load_lds_dwordx4 v177, s[98:99]
	s_add_u32 m0, s45, 0xe000
	v_mfma_f32_16x16x32_bf16 v[16:19], v[234:237], v[206:209], v[16:19]
	global_load_lds_dwordx4 v177, s[100:101]
	v_mfma_f32_16x16x32_bf16 v[12:15], v[238:241], v[194:197], v[12:15]
	v_mfma_f32_16x16x32_bf16 v[8:11], v[238:241], v[198:201], v[8:11]
	v_mfma_f32_16x16x32_bf16 v[4:7], v[238:241], v[202:205], v[4:7]
	v_mfma_f32_16x16x32_bf16 v[0:3], v[238:241], v[206:209], v[0:3]
	s_add_u32 s98, s98, 0x80
	s_addc_u32 s99, s99, 0
	s_add_u32 s100, s100, 0x80
	s_addc_u32 s101, s101, 0
	s_branch .Lg4_half1
.Lg4_nostage0:
	v_mfma_f32_16x16x32_bf16 v[44:47], v[230:233], v[194:197], v[44:47]
	v_mfma_f32_16x16x32_bf16 v[40:43], v[230:233], v[198:201], v[40:43]
	v_mfma_f32_16x16x32_bf16 v[36:39], v[230:233], v[202:205], v[36:39]
	v_mfma_f32_16x16x32_bf16 v[32:35], v[230:233], v[206:209], v[32:35]
	v_mfma_f32_16x16x32_bf16 v[28:31], v[234:237], v[194:197], v[28:31]
	v_mfma_f32_16x16x32_bf16 v[24:27], v[234:237], v[198:201], v[24:27]
	v_mfma_f32_16x16x32_bf16 v[20:23], v[234:237], v[202:205], v[20:23]
	v_mfma_f32_16x16x32_bf16 v[16:19], v[234:237], v[206:209], v[16:19]
	v_mfma_f32_16x16x32_bf16 v[12:15], v[238:241], v[194:197], v[12:15]
	v_mfma_f32_16x16x32_bf16 v[8:11], v[238:241], v[198:201], v[8:11]
	v_mfma_f32_16x16x32_bf16 v[4:7], v[238:241], v[202:205], v[4:7]
	v_mfma_f32_16x16x32_bf16 v[0:3], v[238:241], v[206:209], v[0:3]
.Lg4_half1:
	ds_read_b128 v[222:225], v166
	ds_read_b128 v[226:229], v167
	ds_read_b128 v[230:233], v168
	s_waitcnt lgkmcnt(5)
	v_mfma_f32_16x16x32_bf16 v[124:127], v[210:213], v[178:181], v[124:127]
	v_mfma_f32_16x16x32_bf16 v[120:123], v[210:213], v[182:185], v[120:123]
	v_mfma_f32_16x16x32_bf16 v[116:119], v[210:213], v[186:189], v[116:119]
	v_mfma_f32_16x16x32_bf16 v[112:115], v[210:213], v[190:193], v[112:115]
	ds_read_b128 v[234:237], v169
	s_waitcnt lgkmcnt(5)
	v_mfma_f32_16x16x32_bf16 v[108:111], v[214:217], v[178:181], v[108:111]
	v_mfma_f32_16x16x32_bf16 v[104:107], v[214:217], v[182:185], v[104:107]
	v_mfma_f32_16x16x32_bf16 v[100:103], v[214:217], v[186:189], v[100:103]
	v_mfma_f32_16x16x32_bf16 v[96:99], v[214:217], v[190:193], v[96:99]
	ds_read_b128 v[238:241], v170
	ds_read_b128 v[194:197], v164 offset:33792
	s_waitcnt lgkmcnt(6)
	v_mfma_f32_16x16x32_bf16 v[92:95], v[218:221], v[178:181], v[92:95]
	v_mfma_f32_16x16x32_bf16 v[88:91], v[218:221], v[182:185], v[88:91]
	v_mfma_f32_16x16x32_bf16 v[84:87], v[218:221], v[186:189], v[84:87]
	v_mfma_f32_16x16x32_bf16 v[80:83], v[218:221], v[190:193], v[80:83]
	ds_read_b128 v[210:213], v172 offset:1024
	ds_read_b128 v[198:201], v164 offset:35840
	s_waitcnt lgkmcnt(7)
	v_mfma_f32_16x16x32_bf16 v[76:79], v[222:225], v[178:181], v[76:79]
	v_mfma_f32_16x16x32_bf16 v[72:75], v[222:225], v[182:185], v[72:75]
	v_mfma_f32_16x16x32_bf16 v[68:71], v[222:225], v[186:189], v[68:71]
	v_mfma_f32_16x16x32_bf16 v[64:67], v[222:225], v[190:193], v[64:67]
	ds_read_b128 v[214:217], v173 offset:1024
	ds_read_b128 v[202:205], v164 offset:37888
	s_waitcnt lgkmcnt(8)
	v_mfma_f32_16x16x32_bf16 v[60:63], v[226:229], v[178:181], v[60:63]
	v_mfma_f32_16x16x32_bf16 v[56:59], v[226:229], v[182:185], v[56:59]
	v_mfma_f32_16x16x32_bf16 v[52:55], v[226:229], v[186:189], v[52:55]
	v_mfma_f32_16x16x32_bf16 v[48:51], v[226:229], v[190:193], v[48:51]
	ds_read_b128 v[218:221], v165 offset:1024
	ds_read_b128 v[206:209], v164 offset:39936
	s_waitcnt lgkmcnt(9)
	v_mfma_f32_16x16x32_bf16 v[44:47], v[230:233], v[178:181], v[44:47]
	v_mfma_f32_16x16x32_bf16 v[40:43], v[230:233], v[182:185], v[40:43]
	v_mfma_f32_16x16x32_bf16 v[36:39], v[230:233], v[186:189], v[36:39]
	v_mfma_f32_16x16x32_bf16 v[32:35], v[230:233], v[190:193], v[32:35]
	ds_read_b128 v[222:225], v166 offset:1024
	s_waitcnt lgkmcnt(9)
	v_mfma_f32_16x16x32_bf16 v[28:31], v[234:237], v[178:181], v[28:31]
	v_mfma_f32_16x16x32_bf16 v[24:27], v[234:237], v[182:185], v[24:27]
	v_mfma_f32_16x16x32_bf16 v[20:23], v[234:237], v[186:189], v[20:23]
	v_mfma_f32_16x16x32_bf16 v[16:19], v[234:237], v[190:193], v[16:19]
	ds_read_b128 v[226:229], v167 offset:1024
	s_waitcnt lgkmcnt(9)
	v_mfma_f32_16x16x32_bf16 v[12:15], v[238:241], v[178:181], v[12:15]
	v_mfma_f32_16x16x32_bf16 v[8:11], v[238:241], v[182:185], v[8:11]
	v_mfma_f32_16x16x32_bf16 v[4:7], v[238:241], v[186:189], v[4:7]
	v_mfma_f32_16x16x32_bf16 v[0:3], v[238:241], v[190:193], v[0:3]
	ds_read_b128 v[230:233], v168 offset:1024
	s_waitcnt lgkmcnt(3)
	v_mfma_f32_16x16x32_bf16 v[124:127], v[210:213], v[194:197], v[124:127]
	v_mfma_f32_16x16x32_bf16 v[120:123], v[210:213], v[198:201], v[120:123]
	v_mfma_f32_16x16x32_bf16 v[116:119], v[210:213], v[202:205], v[116:119]
	v_mfma_f32_16x16x32_bf16 v[112:115], v[210:213], v[206:209], v[112:115]
	ds_read_b128 v[234:237], v169 offset:1024
	v_mfma_f32_16x16x32_bf16 v[108:111], v[214:217], v[194:197], v[108:111]
	v_mfma_f32_16x16x32_bf16 v[104:107], v[214:217], v[198:201], v[104:107]
	v_mfma_f32_16x16x32_bf16 v[100:103], v[214:217], v[202:205], v[100:103]
	v_mfma_f32_16x16x32_bf16 v[96:99], v[214:217], v[206:209], v[96:99]
	ds_read_b128 v[238:241], v170 offset:1024
	v_mfma_f32_16x16x32_bf16 v[92:95], v[218:221], v[194:197], v[92:95]
	v_mfma_f32_16x16x32_bf16 v[88:91], v[218:221], v[198:201], v[88:91]
	v_mfma_f32_16x16x32_bf16 v[84:87], v[218:221], v[202:205], v[84:87]
	v_mfma_f32_16x16x32_bf16 v[80:83], v[218:221], v[206:209], v[80:83]
	s_waitcnt lgkmcnt(4)
	v_mfma_f32_16x16x32_bf16 v[76:79], v[222:225], v[194:197], v[76:79]
	v_mfma_f32_16x16x32_bf16 v[72:75], v[222:225], v[198:201], v[72:75]
	v_mfma_f32_16x16x32_bf16 v[68:71], v[222:225], v[202:205], v[68:71]
	v_mfma_f32_16x16x32_bf16 v[64:67], v[222:225], v[206:209], v[64:67]
	s_waitcnt lgkmcnt(3)
	v_mfma_f32_16x16x32_bf16 v[60:63], v[226:229], v[194:197], v[60:63]
	v_mfma_f32_16x16x32_bf16 v[56:59], v[226:229], v[198:201], v[56:59]
	v_mfma_f32_16x16x32_bf16 v[52:55], v[226:229], v[202:205], v[52:55]
	v_mfma_f32_16x16x32_bf16 v[48:51], v[226:229], v[206:209], v[48:51]
	s_waitcnt lgkmcnt(0)
	s_waitcnt vmcnt(0)
	s_barrier
	s_cmp_gt_u32 s1, 13
	s_cbranch_scc1 .Lg4_last
	ds_read_b128 v[178:181], v155 offset:32768
	ds_read_b128 v[182:185], v155 offset:34816
	ds_read_b128 v[186:189], v155 offset:36864
	ds_read_b128 v[190:193], v155 offset:38912
	ds_read_b128 v[210:213], v156
	ds_read_b128 v[214:217], v157
	ds_read_b128 v[218:221], v158
	s_add_u32 m0, s45, 0x10400
	v_mfma_f32_16x16x32_bf16 v[44:47], v[230:233], v[194:197], v[44:47]
	global_load_lds_dwordx4 v174, s[98:99]
	s_add_u32 m0, s45, 0x18400
	v_mfma_f32_16x16x32_bf16 v[40:43], v[230:233], v[198:201], v[40:43]
	global_load_lds_dwordx4 v174, s[100:101]
	s_add_u32 m0, s45, 0x12400
	v_mfma_f32_16x16x32_bf16 v[36:39], v[230:233], v[202:205], v[36:39]
	global_load_lds_dwordx4 v175, s[98:99]
	s_add_u32 m0, s45, 0x1a400
	v_mfma_f32_16x16x32_bf16 v[32:35], v[230:233], v[206:209], v[32:35]
	global_load_lds_dwordx4 v175, s[100:101]
	s_add_u32 m0, s45, 0x14400
	v_mfma_f32_16x16x32_bf16 v[28:31], v[234:237], v[194:197], v[28:31]
	global_load_lds_dwordx4 v176, s[98:99]
	s_add_u32 m0, s45, 0x1c400
	v_mfma_f32_16x16x32_bf16 v[24:27], v[234:237], v[198:201], v[24:27]
	global_load_lds_dwordx4 v176, s[100:101]
	s_add_u32 m0, s45, 0x16400
	v_mfma_f32_16x16x32_bf16 v[20:23], v[234:237], v[202:205], v[20:23]
	global_load_lds_dwordx4 v177, s[98:99]
	s_add_u32 m0, s45, 0x1e400
	v_mfma_f32_16x16x32_bf16 v[16:19], v[234:237], v[206:209], v[16:19]
	global_load_lds_dwordx4 v177, s[100:101]
	v_mfma_f32_16x16x32_bf16 v[12:15], v[238:241], v[194:197], v[12:15]
	v_mfma_f32_16x16x32_bf16 v[8:11], v[238:241], v[198:201], v[8:11]
	v_mfma_f32_16x16x32_bf16 v[4:7], v[238:241], v[202:205], v[4:7]
	v_mfma_f32_16x16x32_bf16 v[0:3], v[238:241], v[206:209], v[0:3]
	s_add_u32 s98, s98, 0x80
	s_addc_u32 s99, s99, 0
	s_add_u32 s100, s100, 0x80
	s_addc_u32 s101, s101, 0
	s_add_i32 s1, s1, 2
	s_branch .LBB0_1788
.Lg4_last:
	v_mfma_f32_16x16x32_bf16 v[44:47], v[230:233], v[194:197], v[44:47]
	v_mfma_f32_16x16x32_bf16 v[40:43], v[230:233], v[198:201], v[40:43]
	v_mfma_f32_16x16x32_bf16 v[36:39], v[230:233], v[202:205], v[36:39]
	v_mfma_f32_16x16x32_bf16 v[32:35], v[230:233], v[206:209], v[32:35]
	v_mfma_f32_16x16x32_bf16 v[28:31], v[234:237], v[194:197], v[28:31]
	v_mfma_f32_16x16x32_bf16 v[24:27], v[234:237], v[198:201], v[24:27]
	v_mfma_f32_16x16x32_bf16 v[20:23], v[234:237], v[202:205], v[20:23]
	v_mfma_f32_16x16x32_bf16 v[16:19], v[234:237], v[206:209], v[16:19]
	v_mfma_f32_16x16x32_bf16 v[12:15], v[238:241], v[194:197], v[12:15]
	v_mfma_f32_16x16x32_bf16 v[8:11], v[238:241], v[198:201], v[8:11]
	v_mfma_f32_16x16x32_bf16 v[4:7], v[238:241], v[202:205], v[4:7]
	v_mfma_f32_16x16x32_bf16 v[0:3], v[238:241], v[206:209], v[0:3]
	s_nop 15
	s_nop 15
